# short-conv chunk loop: 8 iterations unrolled and software-pipelined, loads of iteration k+1 issued into a second register set before iteration k is computed
# speedup vs baseline: 1.0111x; 1.0093x over previous
.LBB0_742:
	s_or_b64 exec, exec, s[14:15]
	s_waitcnt lgkmcnt(0)
	s_barrier
	v_mov_b32_e32 v0, s17
	ds_read_b32 v0, v0
	s_waitcnt lgkmcnt(0)
	s_barrier
	s_movk_i32 s14, 0x3ff
	s_waitcnt lgkmcnt(0)
	v_cmp_lt_u32_e32 vcc, s14, v0
	s_mov_b64 s[14:15], -1
	s_cbranch_vccnz .LBB0_739
	s_mov_b32 s14, -1
	s_mov_b32 s18, 0
	v_mbcnt_lo_u32_b32 v1, s14, 0
	v_mbcnt_hi_u32_b32 v1, s14, v1
	v_or_b32_e32 v1, s33, v1
	s_mov_b32 s19, 0
	v_ashrrev_i32_e32 v3, 3, v1
	v_and_b32_e32 v3, -8, v3
	v_lshrrev_b32_e32 v2, 4, v1
	v_lshl_add_u32 v0, v0, 6, v3
	v_and_or_b32 v20, v2, 3, v0
	v_lshlrev_b32_e32 v0, 3, v1
	v_and_b32_e32 v1, 64, v239
	v_and_b32_e32 v21, 0x78, v0
	v_xor_b32_e32 v0, 1, v239
	v_add_u32_e32 v1, 64, v1
	v_cmp_lt_i32_e32 vcc, v0, v1
	s_nop 1
	v_cndmask_b32_e32 v0, v239, v0, vcc
	v_lshlrev_b32_e32 v22, 2, v0
	v_xor_b32_e32 v0, 2, v239
	v_cmp_lt_i32_e32 vcc, v0, v1
	s_nop 1
	v_cndmask_b32_e32 v0, v239, v0, vcc
	v_lshlrev_b32_e32 v23, 2, v0
	v_xor_b32_e32 v0, 4, v239
	v_cmp_lt_i32_e32 vcc, v0, v1
	s_nop 1
	v_cndmask_b32_e32 v0, v239, v0, vcc
	v_lshlrev_b32_e32 v24, 2, v0
	v_xor_b32_e32 v0, 8, v239
	v_cmp_lt_i32_e32 vcc, v0, v1
	s_nop 1
	v_cndmask_b32_e32 v0, v239, v0, vcc
	v_lshlrev_b32_e32 v25, 2, v0
	v_mov_b64_e32 v[54:55], 0
	v_mov_b64_e32 v[154:155], 0
	v_mov_b64_e32 v[56:57], 0
	v_mov_b64_e32 v[156:157], 0
	v_mov_b64_e32 v[58:59], 0
	v_mov_b64_e32 v[158:159], 0
	v_mov_b64_e32 v[60:61], 0
	v_mov_b64_e32 v[160:161], 0
	v_mov_b64_e32 v[62:63], 0
	v_mov_b64_e32 v[162:163], 0
	v_mov_b64_e32 v[64:65], 0
	v_mov_b64_e32 v[164:165], 0
	v_mov_b64_e32 v[66:67], 0
	v_mov_b64_e32 v[166:167], 0
	v_mov_b64_e32 v[68:69], 0
	v_mov_b64_e32 v[168:169], 0
	v_mov_b64_e32 v[76:77], 0
	v_mov_b64_e32 v[202:203], 0
	v_mov_b64_e32 v[78:79], 0
	v_mov_b64_e32 v[204:205], 0
	v_mov_b64_e32 v[80:81], 0
	v_mov_b64_e32 v[206:207], 0
	v_mov_b64_e32 v[82:83], 0
	v_mov_b64_e32 v[208:209], 0
	s_mov_b32 s20, 0
	s_movk_i32 s14, 0x0
	v_or_b32_e32 v44, s20, v20
	v_or_b32_e32 v6, s14, v21
	v_mov_b64_e32 v[0:1], s[6:7]
	v_mad_i64_i32 v[0:1], s[14:15], v44, s58, v[0:1]
	v_lshlrev_b32_e32 v192, 1, v6
	v_lshlrev_b32_e32 v6, 2, v6
	v_mov_b32_e32 v7, v193
	v_lshl_add_u64 v[12:13], v[0:1], 0, v[192:193]
	v_lshl_add_u64 v[14:15], s[8:9], 0, v[6:7]
	v_bitop3_b32 v5, s20, v246, v20 bitop3:0xc8
	v_mov_b64_e32 v[50:51], 0
	v_mov_b64_e32 v[52:53], 0
	v_mov_b64_e32 v[70:71], 0
	v_mov_b64_e32 v[72:73], 0
	global_load_dwordx4 v[0:3], v[12:13], off
	global_load_dwordx4 v[16:19], v[12:13], off offset:1024
	global_load_dwordx4 v[26:29], v[12:13], off offset:2048
	v_add_co_u32_e32 v8, vcc, 0x1000, v14
	s_nop 1
	v_addc_co_u32_e32 v9, vcc, 0, v15, vcc
	global_load_dwordx4 v[30:33], v[8:9], off offset:16
	global_load_dwordx4 v[8:11], v[8:9], off
	v_cmp_ne_u32_e32 vcc, 0, v5
	s_and_saveexec_b64 s[14:15], vcc
	global_load_dwordx4 v[50:53], v[12:13], off offset:-2048
	global_load_dwordx4 v[54:57], v[12:13], off offset:-1024
	global_load_dwordx4 v[58:61], v[14:15], off offset:2048
	global_load_dwordx4 v[62:65], v[14:15], off offset:2064
	s_or_b64 exec, exec, s[14:15]
	v_cmp_lt_u32_e32 vcc, 1, v5
	s_and_saveexec_b64 s[14:15], vcc
	v_add_co_u32_e32 v74, vcc, 0xfffff000, v12
	s_nop 1
	v_addc_co_u32_e32 v75, vcc, -1, v13, vcc
	global_load_dwordx4 v[66:69], v[12:13], off offset:-4096
	global_load_dwordx4 v[70:73], v[74:75], off offset:-1024
	global_load_dwordx4 v[76:79], v[14:15], off offset:16
	global_load_dwordx4 v[80:83], v[14:15], off
	s_or_b64 exec, exec, s[14:15]
	global_load_dwordx4 v[84:87], v6, s[10:11] offset:16
	global_load_dwordx4 v[88:91], v6, s[10:11]
	v_ashrrev_i32_e32 v45, 31, v44
	v_lshlrev_b64 v[44:45], 11, v[44:45]
	v_lshl_add_u64 v[44:45], s[4:5], 0, v[44:45]
	v_lshl_add_u64 v[44:45], v[44:45], 0, v[192:193]
	v_add_co_u32_e32 v44, vcc, 0xec00000, v44
	s_nop 1
	v_addc_co_u32_e32 v45, vcc, 0, v45, vcc
	s_mov_b32 s20, 0
	s_movk_i32 s14, 0x80
	v_or_b32_e32 v148, s20, v20
	v_or_b32_e32 v126, s14, v21
	v_mov_b64_e32 v[120:121], s[6:7]
	v_mad_i64_i32 v[120:121], s[14:15], v148, s58, v[120:121]
	v_lshlrev_b32_e32 v192, 1, v126
	v_lshlrev_b32_e32 v126, 2, v126
	v_mov_b32_e32 v127, v193
	v_lshl_add_u64 v[132:133], v[120:121], 0, v[192:193]
	v_lshl_add_u64 v[134:135], s[8:9], 0, v[126:127]
	v_bitop3_b32 v124, s20, v246, v20 bitop3:0xc8
	v_mov_b64_e32 v[150:151], 0
	v_mov_b64_e32 v[152:153], 0
	v_mov_b64_e32 v[170:171], 0
	v_mov_b64_e32 v[172:173], 0
	global_load_dwordx4 v[120:123], v[132:133], off
	global_load_dwordx4 v[136:139], v[132:133], off offset:1024
	global_load_dwordx4 v[140:143], v[132:133], off offset:2048
	v_add_co_u32_e32 v128, vcc, 0x1000, v134
	s_nop 1
	v_addc_co_u32_e32 v129, vcc, 0, v135, vcc
	global_load_dwordx4 v[144:147], v[128:129], off offset:16
	global_load_dwordx4 v[128:131], v[128:129], off
	v_cmp_ne_u32_e32 vcc, 0, v124
	s_and_saveexec_b64 s[14:15], vcc
	global_load_dwordx4 v[150:153], v[132:133], off offset:-2048
	global_load_dwordx4 v[154:157], v[132:133], off offset:-1024
	global_load_dwordx4 v[158:161], v[134:135], off offset:2048
	global_load_dwordx4 v[162:165], v[134:135], off offset:2064
	s_or_b64 exec, exec, s[14:15]
	v_cmp_lt_u32_e32 vcc, 1, v124
	s_and_saveexec_b64 s[14:15], vcc
	v_add_co_u32_e32 v174, vcc, 0xfffff000, v132
	s_nop 1
	v_addc_co_u32_e32 v175, vcc, -1, v133, vcc
	global_load_dwordx4 v[166:169], v[132:133], off offset:-4096
	global_load_dwordx4 v[170:173], v[174:175], off offset:-1024
	global_load_dwordx4 v[202:205], v[134:135], off offset:16
	global_load_dwordx4 v[206:209], v[134:135], off
	s_or_b64 exec, exec, s[14:15]
	global_load_dwordx4 v[210:213], v126, s[10:11] offset:16
	global_load_dwordx4 v[214:217], v126, s[10:11]
	v_ashrrev_i32_e32 v149, 31, v148
	v_lshlrev_b64 v[148:149], 11, v[148:149]
	v_lshl_add_u64 v[148:149], s[4:5], 0, v[148:149]
	v_lshl_add_u64 v[148:149], v[148:149], 0, v[192:193]
	v_add_co_u32_e32 v148, vcc, 0xec00000, v148
	s_nop 1
	v_addc_co_u32_e32 v149, vcc, 0, v149, vcc
	s_waitcnt vmcnt(15)
	v_lshlrev_b32_e32 v34, 16, v16
	v_and_b32_e32 v35, 0xffff0000, v16
	v_lshlrev_b32_e32 v36, 16, v26
	v_and_b32_e32 v37, 0xffff0000, v26
	v_pk_mul_f32 v[34:35], v[34:35], v[36:37]
	v_pk_fma_f32 v[92:93], v[8:9], v[34:35], 0 op_sel_hi:[1,1,0]
	v_lshlrev_b32_e32 v38, 16, v17
	v_and_b32_e32 v39, 0xffff0000, v17
	v_lshlrev_b32_e32 v40, 16, v27
	v_and_b32_e32 v41, 0xffff0000, v27
	v_pk_mul_f32 v[38:39], v[38:39], v[40:41]
	v_pk_fma_f32 v[94:95], v[10:11], v[38:39], 0 op_sel_hi:[1,1,0]
	v_lshlrev_b32_e32 v34, 16, v18
	v_and_b32_e32 v35, 0xffff0000, v18
	v_lshlrev_b32_e32 v36, 16, v28
	v_and_b32_e32 v37, 0xffff0000, v28
	v_pk_mul_f32 v[34:35], v[34:35], v[36:37]
	v_pk_fma_f32 v[96:97], v[30:31], v[34:35], 0 op_sel_hi:[1,1,0]
	v_lshlrev_b32_e32 v38, 16, v19
	v_and_b32_e32 v39, 0xffff0000, v19
	v_lshlrev_b32_e32 v40, 16, v29
	v_and_b32_e32 v41, 0xffff0000, v29
	v_pk_mul_f32 v[38:39], v[38:39], v[40:41]
	v_pk_fma_f32 v[98:99], v[32:33], v[38:39], 0 op_sel_hi:[1,1,0]
	v_lshlrev_b32_e32 v34, 16, v50
	v_and_b32_e32 v35, 0xffff0000, v50
	v_lshlrev_b32_e32 v36, 16, v54
	v_and_b32_e32 v37, 0xffff0000, v54
	v_pk_mul_f32 v[34:35], v[34:35], v[36:37]
	v_pk_fma_f32 v[92:93], v[58:59], v[34:35], v[92:93]
	v_lshlrev_b32_e32 v38, 16, v51
	v_and_b32_e32 v39, 0xffff0000, v51
	v_lshlrev_b32_e32 v40, 16, v55
	v_and_b32_e32 v41, 0xffff0000, v55
	v_pk_mul_f32 v[38:39], v[38:39], v[40:41]
	v_pk_fma_f32 v[94:95], v[60:61], v[38:39], v[94:95]
	v_lshlrev_b32_e32 v34, 16, v52
	v_and_b32_e32 v35, 0xffff0000, v52
	v_lshlrev_b32_e32 v36, 16, v56
	v_and_b32_e32 v37, 0xffff0000, v56
	v_pk_mul_f32 v[34:35], v[34:35], v[36:37]
	v_pk_fma_f32 v[96:97], v[62:63], v[34:35], v[96:97]
	v_lshlrev_b32_e32 v38, 16, v53
	v_and_b32_e32 v39, 0xffff0000, v53
	v_lshlrev_b32_e32 v40, 16, v57
	v_and_b32_e32 v41, 0xffff0000, v57
	v_pk_mul_f32 v[38:39], v[38:39], v[40:41]
	v_pk_fma_f32 v[98:99], v[64:65], v[38:39], v[98:99]
	v_lshlrev_b32_e32 v34, 16, v70
	v_and_b32_e32 v35, 0xffff0000, v70
	v_lshlrev_b32_e32 v36, 16, v66
	v_and_b32_e32 v37, 0xffff0000, v66
	v_pk_mul_f32 v[34:35], v[34:35], v[36:37]
	v_pk_fma_f32 v[92:93], v[80:81], v[34:35], v[92:93]
	v_lshlrev_b32_e32 v38, 16, v71
	v_and_b32_e32 v39, 0xffff0000, v71
	v_lshlrev_b32_e32 v40, 16, v67
	v_and_b32_e32 v41, 0xffff0000, v67
	v_pk_mul_f32 v[38:39], v[38:39], v[40:41]
	v_pk_fma_f32 v[94:95], v[82:83], v[38:39], v[94:95]
	v_lshlrev_b32_e32 v34, 16, v72
	v_and_b32_e32 v35, 0xffff0000, v72
	v_lshlrev_b32_e32 v36, 16, v68
	v_and_b32_e32 v37, 0xffff0000, v68
	v_pk_mul_f32 v[34:35], v[34:35], v[36:37]
	v_pk_fma_f32 v[96:97], v[76:77], v[34:35], v[96:97]
	v_lshlrev_b32_e32 v38, 16, v73
	v_and_b32_e32 v39, 0xffff0000, v73
	v_lshlrev_b32_e32 v40, 16, v69
	v_and_b32_e32 v41, 0xffff0000, v69
	v_pk_mul_f32 v[38:39], v[38:39], v[40:41]
	v_pk_fma_f32 v[98:99], v[78:79], v[38:39], v[98:99]
	v_lshlrev_b32_e32 v34, 16, v0
	v_and_b32_e32 v35, 0xffff0000, v0
	v_pk_mul_f32 v[100:101], v[92:93], v[34:35]
	v_lshlrev_b32_e32 v34, 16, v1
	v_and_b32_e32 v35, 0xffff0000, v1
	v_pk_mul_f32 v[102:103], v[94:95], v[34:35]
	v_lshlrev_b32_e32 v34, 16, v2
	v_and_b32_e32 v35, 0xffff0000, v2
	v_pk_mul_f32 v[104:105], v[96:97], v[34:35]
	v_lshlrev_b32_e32 v34, 16, v3
	v_and_b32_e32 v35, 0xffff0000, v3
	v_pk_mul_f32 v[106:107], v[98:99], v[34:35]
	v_pk_mul_f32 v[34:35], v[100:101], v[100:101]
	v_pk_mul_f32 v[36:37], v[102:103], v[102:103]
	v_add_f32_e32 v42, v34, v35
	v_add_f32_e32 v42, v36, v42
	v_pk_mul_f32 v[38:39], v[104:105], v[104:105]
	v_add_f32_e32 v42, v37, v42
	v_add_f32_e32 v42, v38, v42
	v_pk_mul_f32 v[40:41], v[106:107], v[106:107]
	v_add_f32_e32 v42, v39, v42
	v_add_f32_e32 v42, v40, v42
	v_add_f32_e32 v42, v41, v42
	ds_bpermute_b32 v43, v22, v42
	s_waitcnt lgkmcnt(0)
	v_add_f32_e32 v42, v42, v43
	ds_bpermute_b32 v43, v23, v42
	s_waitcnt lgkmcnt(0)
	v_add_f32_e32 v42, v42, v43
	ds_bpermute_b32 v43, v24, v42
	s_waitcnt lgkmcnt(0)
	v_add_f32_e32 v42, v42, v43
	ds_bpermute_b32 v43, v25, v42
	s_waitcnt lgkmcnt(0)
	v_add_f32_e32 v42, v42, v43
	v_fmamk_f32 v42, v42, 0x3c000000, v238
	v_cmp_gt_f32_e32 vcc, s66, v42
	v_mul_f32_e32 v43, 0x4b800000, v42
	s_nop 0
	v_cndmask_b32_e32 v42, v42, v43, vcc
	v_rsq_f32_e32 v42, v42
	s_nop 0
	v_mul_f32_e32 v43, 0x45800000, v42
	v_cndmask_b32_e32 v42, v42, v43, vcc
	v_pk_mul_f32 v[100:101], v[100:101], v[42:43] op_sel_hi:[1,0]
	v_pk_mul_f32 v[102:103], v[102:103], v[42:43] op_sel_hi:[1,0]
	v_pk_mul_f32 v[104:105], v[104:105], v[42:43] op_sel_hi:[1,0]
	v_pk_mul_f32 v[106:107], v[106:107], v[42:43] op_sel_hi:[1,0]
	v_pk_mul_f32 v[100:101], v[88:89], v[100:101]
	v_pk_mul_f32 v[102:103], v[90:91], v[102:103]
	v_pk_mul_f32 v[104:105], v[84:85], v[104:105]
	v_pk_mul_f32 v[106:107], v[86:87], v[106:107]
	v_cvt_pk_bf16_f32 v0, v100, v101
	v_cvt_pk_bf16_f32 v1, v102, v103
	v_cvt_pk_bf16_f32 v2, v104, v105
	v_cvt_pk_bf16_f32 v3, v106, v107
	global_store_dwordx4 v[44:45], v[0:3], off offset:1024
	s_mov_b32 s20, 0
	s_movk_i32 s14, 0x100
	v_or_b32_e32 v44, s20, v20
	v_or_b32_e32 v6, s14, v21
	v_mov_b64_e32 v[0:1], s[6:7]
	v_mad_i64_i32 v[0:1], s[14:15], v44, s58, v[0:1]
	v_lshlrev_b32_e32 v192, 1, v6
	v_lshlrev_b32_e32 v6, 2, v6
	v_mov_b32_e32 v7, v193
	v_lshl_add_u64 v[12:13], v[0:1], 0, v[192:193]
	v_lshl_add_u64 v[14:15], s[8:9], 0, v[6:7]
	v_bitop3_b32 v5, s20, v246, v20 bitop3:0xc8
	v_mov_b64_e32 v[50:51], 0
	v_mov_b64_e32 v[52:53], 0
	v_mov_b64_e32 v[70:71], 0
	v_mov_b64_e32 v[72:73], 0
	global_load_dwordx4 v[0:3], v[12:13], off
	global_load_dwordx4 v[16:19], v[12:13], off offset:1024
	global_load_dwordx4 v[26:29], v[12:13], off offset:2048
	v_add_co_u32_e32 v8, vcc, 0x1000, v14
	s_nop 1
	v_addc_co_u32_e32 v9, vcc, 0, v15, vcc
	global_load_dwordx4 v[30:33], v[8:9], off offset:16
	global_load_dwordx4 v[8:11], v[8:9], off
	v_cmp_ne_u32_e32 vcc, 0, v5
	s_and_saveexec_b64 s[14:15], vcc
	global_load_dwordx4 v[50:53], v[12:13], off offset:-2048
	global_load_dwordx4 v[54:57], v[12:13], off offset:-1024
	global_load_dwordx4 v[58:61], v[14:15], off offset:2048
	global_load_dwordx4 v[62:65], v[14:15], off offset:2064
	s_or_b64 exec, exec, s[14:15]
	v_cmp_lt_u32_e32 vcc, 1, v5
	s_and_saveexec_b64 s[14:15], vcc
	v_add_co_u32_e32 v74, vcc, 0xfffff000, v12
	s_nop 1
	v_addc_co_u32_e32 v75, vcc, -1, v13, vcc
	global_load_dwordx4 v[66:69], v[12:13], off offset:-4096
	global_load_dwordx4 v[70:73], v[74:75], off offset:-1024
	global_load_dwordx4 v[76:79], v[14:15], off offset:16
	global_load_dwordx4 v[80:83], v[14:15], off
	s_or_b64 exec, exec, s[14:15]
	global_load_dwordx4 v[84:87], v6, s[10:11] offset:16
	global_load_dwordx4 v[88:91], v6, s[10:11]
	v_ashrrev_i32_e32 v45, 31, v44
	v_lshlrev_b64 v[44:45], 11, v[44:45]
	v_lshl_add_u64 v[44:45], s[4:5], 0, v[44:45]
	v_lshl_add_u64 v[44:45], v[44:45], 0, v[192:193]
	v_add_co_u32_e32 v44, vcc, 0xec00000, v44
	s_nop 1
	v_addc_co_u32_e32 v45, vcc, 0, v45, vcc
	s_waitcnt vmcnt(16)
	v_lshlrev_b32_e32 v34, 16, v136
	v_and_b32_e32 v35, 0xffff0000, v136
	v_lshlrev_b32_e32 v36, 16, v140
	v_and_b32_e32 v37, 0xffff0000, v140
	v_pk_mul_f32 v[34:35], v[34:35], v[36:37]
	v_pk_fma_f32 v[92:93], v[128:129], v[34:35], 0 op_sel_hi:[1,1,0]
	v_lshlrev_b32_e32 v38, 16, v137
	v_and_b32_e32 v39, 0xffff0000, v137
	v_lshlrev_b32_e32 v40, 16, v141
	v_and_b32_e32 v41, 0xffff0000, v141
	v_pk_mul_f32 v[38:39], v[38:39], v[40:41]
	v_pk_fma_f32 v[94:95], v[130:131], v[38:39], 0 op_sel_hi:[1,1,0]
	v_lshlrev_b32_e32 v34, 16, v138
	v_and_b32_e32 v35, 0xffff0000, v138
	v_lshlrev_b32_e32 v36, 16, v142
	v_and_b32_e32 v37, 0xffff0000, v142
	v_pk_mul_f32 v[34:35], v[34:35], v[36:37]
	v_pk_fma_f32 v[96:97], v[144:145], v[34:35], 0 op_sel_hi:[1,1,0]
	v_lshlrev_b32_e32 v38, 16, v139
	v_and_b32_e32 v39, 0xffff0000, v139
	v_lshlrev_b32_e32 v40, 16, v143
	v_and_b32_e32 v41, 0xffff0000, v143
	v_pk_mul_f32 v[38:39], v[38:39], v[40:41]
	v_pk_fma_f32 v[98:99], v[146:147], v[38:39], 0 op_sel_hi:[1,1,0]
	v_lshlrev_b32_e32 v34, 16, v150
	v_and_b32_e32 v35, 0xffff0000, v150
	v_lshlrev_b32_e32 v36, 16, v154
	v_and_b32_e32 v37, 0xffff0000, v154
	v_pk_mul_f32 v[34:35], v[34:35], v[36:37]
	v_pk_fma_f32 v[92:93], v[158:159], v[34:35], v[92:93]
	v_lshlrev_b32_e32 v38, 16, v151
	v_and_b32_e32 v39, 0xffff0000, v151
	v_lshlrev_b32_e32 v40, 16, v155
	v_and_b32_e32 v41, 0xffff0000, v155
	v_pk_mul_f32 v[38:39], v[38:39], v[40:41]
	v_pk_fma_f32 v[94:95], v[160:161], v[38:39], v[94:95]
	v_lshlrev_b32_e32 v34, 16, v152
	v_and_b32_e32 v35, 0xffff0000, v152
	v_lshlrev_b32_e32 v36, 16, v156
	v_and_b32_e32 v37, 0xffff0000, v156
	v_pk_mul_f32 v[34:35], v[34:35], v[36:37]
	v_pk_fma_f32 v[96:97], v[162:163], v[34:35], v[96:97]
	v_lshlrev_b32_e32 v38, 16, v153
	v_and_b32_e32 v39, 0xffff0000, v153
	v_lshlrev_b32_e32 v40, 16, v157
	v_and_b32_e32 v41, 0xffff0000, v157
	v_pk_mul_f32 v[38:39], v[38:39], v[40:41]
	v_pk_fma_f32 v[98:99], v[164:165], v[38:39], v[98:99]
	v_lshlrev_b32_e32 v34, 16, v170
	v_and_b32_e32 v35, 0xffff0000, v170
	v_lshlrev_b32_e32 v36, 16, v166
	v_and_b32_e32 v37, 0xffff0000, v166
	v_pk_mul_f32 v[34:35], v[34:35], v[36:37]
	v_pk_fma_f32 v[92:93], v[206:207], v[34:35], v[92:93]
	v_lshlrev_b32_e32 v38, 16, v171
	v_and_b32_e32 v39, 0xffff0000, v171
	v_lshlrev_b32_e32 v40, 16, v167
	v_and_b32_e32 v41, 0xffff0000, v167
	v_pk_mul_f32 v[38:39], v[38:39], v[40:41]
	v_pk_fma_f32 v[94:95], v[208:209], v[38:39], v[94:95]
	v_lshlrev_b32_e32 v34, 16, v172
	v_and_b32_e32 v35, 0xffff0000, v172
	v_lshlrev_b32_e32 v36, 16, v168
	v_and_b32_e32 v37, 0xffff0000, v168
	v_pk_mul_f32 v[34:35], v[34:35], v[36:37]
	v_pk_fma_f32 v[96:97], v[202:203], v[34:35], v[96:97]
	v_lshlrev_b32_e32 v38, 16, v173
	v_and_b32_e32 v39, 0xffff0000, v173
	v_lshlrev_b32_e32 v40, 16, v169
	v_and_b32_e32 v41, 0xffff0000, v169
	v_pk_mul_f32 v[38:39], v[38:39], v[40:41]
	v_pk_fma_f32 v[98:99], v[204:205], v[38:39], v[98:99]
	v_lshlrev_b32_e32 v34, 16, v120
	v_and_b32_e32 v35, 0xffff0000, v120
	v_pk_mul_f32 v[100:101], v[92:93], v[34:35]
	v_lshlrev_b32_e32 v34, 16, v121
	v_and_b32_e32 v35, 0xffff0000, v121
	v_pk_mul_f32 v[102:103], v[94:95], v[34:35]
	v_lshlrev_b32_e32 v34, 16, v122
	v_and_b32_e32 v35, 0xffff0000, v122
	v_pk_mul_f32 v[104:105], v[96:97], v[34:35]
	v_lshlrev_b32_e32 v34, 16, v123
	v_and_b32_e32 v35, 0xffff0000, v123
	v_pk_mul_f32 v[106:107], v[98:99], v[34:35]
	v_pk_mul_f32 v[34:35], v[100:101], v[100:101]
	v_pk_mul_f32 v[36:37], v[102:103], v[102:103]
	v_add_f32_e32 v42, v34, v35
	v_add_f32_e32 v42, v36, v42
	v_pk_mul_f32 v[38:39], v[104:105], v[104:105]
	v_add_f32_e32 v42, v37, v42
	v_add_f32_e32 v42, v38, v42
	v_pk_mul_f32 v[40:41], v[106:107], v[106:107]
	v_add_f32_e32 v42, v39, v42
	v_add_f32_e32 v42, v40, v42
	v_add_f32_e32 v42, v41, v42
	ds_bpermute_b32 v43, v22, v42
	s_waitcnt lgkmcnt(0)
	v_add_f32_e32 v42, v42, v43
	ds_bpermute_b32 v43, v23, v42
	s_waitcnt lgkmcnt(0)
	v_add_f32_e32 v42, v42, v43
	ds_bpermute_b32 v43, v24, v42
	s_waitcnt lgkmcnt(0)
	v_add_f32_e32 v42, v42, v43
	ds_bpermute_b32 v43, v25, v42
	s_waitcnt lgkmcnt(0)
	v_add_f32_e32 v42, v42, v43
	v_fmamk_f32 v42, v42, 0x3c000000, v238
	v_cmp_gt_f32_e32 vcc, s66, v42
	v_mul_f32_e32 v43, 0x4b800000, v42
	s_nop 0
	v_cndmask_b32_e32 v42, v42, v43, vcc
	v_rsq_f32_e32 v42, v42
	s_nop 0
	v_mul_f32_e32 v43, 0x45800000, v42
	v_cndmask_b32_e32 v42, v42, v43, vcc
	v_pk_mul_f32 v[100:101], v[100:101], v[42:43] op_sel_hi:[1,0]
	v_pk_mul_f32 v[102:103], v[102:103], v[42:43] op_sel_hi:[1,0]
	v_pk_mul_f32 v[104:105], v[104:105], v[42:43] op_sel_hi:[1,0]
	v_pk_mul_f32 v[106:107], v[106:107], v[42:43] op_sel_hi:[1,0]
	v_pk_mul_f32 v[100:101], v[214:215], v[100:101]
	v_pk_mul_f32 v[102:103], v[216:217], v[102:103]
	v_pk_mul_f32 v[104:105], v[210:211], v[104:105]
	v_pk_mul_f32 v[106:107], v[212:213], v[106:107]
	v_cvt_pk_bf16_f32 v120, v100, v101
	v_cvt_pk_bf16_f32 v121, v102, v103
	v_cvt_pk_bf16_f32 v122, v104, v105
	v_cvt_pk_bf16_f32 v123, v106, v107
	global_store_dwordx4 v[148:149], v[120:123], off offset:1024
	s_mov_b32 s20, 0
	s_movk_i32 s14, 0x180
	v_or_b32_e32 v148, s20, v20
	v_or_b32_e32 v126, s14, v21
	v_mov_b64_e32 v[120:121], s[6:7]
	v_mad_i64_i32 v[120:121], s[14:15], v148, s58, v[120:121]
	v_lshlrev_b32_e32 v192, 1, v126
	v_lshlrev_b32_e32 v126, 2, v126
	v_mov_b32_e32 v127, v193
	v_lshl_add_u64 v[132:133], v[120:121], 0, v[192:193]
	v_lshl_add_u64 v[134:135], s[8:9], 0, v[126:127]
	v_bitop3_b32 v124, s20, v246, v20 bitop3:0xc8
	v_mov_b64_e32 v[150:151], 0
	v_mov_b64_e32 v[152:153], 0
	v_mov_b64_e32 v[170:171], 0
	v_mov_b64_e32 v[172:173], 0
	global_load_dwordx4 v[120:123], v[132:133], off
	global_load_dwordx4 v[136:139], v[132:133], off offset:1024
	global_load_dwordx4 v[140:143], v[132:133], off offset:2048
	v_add_co_u32_e32 v128, vcc, 0x1000, v134
	s_nop 1
	v_addc_co_u32_e32 v129, vcc, 0, v135, vcc
	global_load_dwordx4 v[144:147], v[128:129], off offset:16
	global_load_dwordx4 v[128:131], v[128:129], off
	v_cmp_ne_u32_e32 vcc, 0, v124
	s_and_saveexec_b64 s[14:15], vcc
	global_load_dwordx4 v[150:153], v[132:133], off offset:-2048
	global_load_dwordx4 v[154:157], v[132:133], off offset:-1024
	global_load_dwordx4 v[158:161], v[134:135], off offset:2048
	global_load_dwordx4 v[162:165], v[134:135], off offset:2064
	s_or_b64 exec, exec, s[14:15]
	v_cmp_lt_u32_e32 vcc, 1, v124
	s_and_saveexec_b64 s[14:15], vcc
	v_add_co_u32_e32 v174, vcc, 0xfffff000, v132
	s_nop 1
	v_addc_co_u32_e32 v175, vcc, -1, v133, vcc
	global_load_dwordx4 v[166:169], v[132:133], off offset:-4096
	global_load_dwordx4 v[170:173], v[174:175], off offset:-1024
	global_load_dwordx4 v[202:205], v[134:135], off offset:16
	global_load_dwordx4 v[206:209], v[134:135], off
	s_or_b64 exec, exec, s[14:15]
	global_load_dwordx4 v[210:213], v126, s[10:11] offset:16
	global_load_dwordx4 v[214:217], v126, s[10:11]
	v_ashrrev_i32_e32 v149, 31, v148
	v_lshlrev_b64 v[148:149], 11, v[148:149]
	v_lshl_add_u64 v[148:149], s[4:5], 0, v[148:149]
	v_lshl_add_u64 v[148:149], v[148:149], 0, v[192:193]
	v_add_co_u32_e32 v148, vcc, 0xec00000, v148
	s_nop 1
	v_addc_co_u32_e32 v149, vcc, 0, v149, vcc
	s_waitcnt vmcnt(16)
	v_lshlrev_b32_e32 v34, 16, v16
	v_and_b32_e32 v35, 0xffff0000, v16
	v_lshlrev_b32_e32 v36, 16, v26
	v_and_b32_e32 v37, 0xffff0000, v26
	v_pk_mul_f32 v[34:35], v[34:35], v[36:37]
	v_pk_fma_f32 v[92:93], v[8:9], v[34:35], 0 op_sel_hi:[1,1,0]
	v_lshlrev_b32_e32 v38, 16, v17
	v_and_b32_e32 v39, 0xffff0000, v17
	v_lshlrev_b32_e32 v40, 16, v27
	v_and_b32_e32 v41, 0xffff0000, v27
	v_pk_mul_f32 v[38:39], v[38:39], v[40:41]
	v_pk_fma_f32 v[94:95], v[10:11], v[38:39], 0 op_sel_hi:[1,1,0]
	v_lshlrev_b32_e32 v34, 16, v18
	v_and_b32_e32 v35, 0xffff0000, v18
	v_lshlrev_b32_e32 v36, 16, v28
	v_and_b32_e32 v37, 0xffff0000, v28
	v_pk_mul_f32 v[34:35], v[34:35], v[36:37]
	v_pk_fma_f32 v[96:97], v[30:31], v[34:35], 0 op_sel_hi:[1,1,0]
	v_lshlrev_b32_e32 v38, 16, v19
	v_and_b32_e32 v39, 0xffff0000, v19
	v_lshlrev_b32_e32 v40, 16, v29
	v_and_b32_e32 v41, 0xffff0000, v29
	v_pk_mul_f32 v[38:39], v[38:39], v[40:41]
	v_pk_fma_f32 v[98:99], v[32:33], v[38:39], 0 op_sel_hi:[1,1,0]
	v_lshlrev_b32_e32 v34, 16, v50
	v_and_b32_e32 v35, 0xffff0000, v50
	v_lshlrev_b32_e32 v36, 16, v54
	v_and_b32_e32 v37, 0xffff0000, v54
	v_pk_mul_f32 v[34:35], v[34:35], v[36:37]
	v_pk_fma_f32 v[92:93], v[58:59], v[34:35], v[92:93]
	v_lshlrev_b32_e32 v38, 16, v51
	v_and_b32_e32 v39, 0xffff0000, v51
	v_lshlrev_b32_e32 v40, 16, v55
	v_and_b32_e32 v41, 0xffff0000, v55
	v_pk_mul_f32 v[38:39], v[38:39], v[40:41]
	v_pk_fma_f32 v[94:95], v[60:61], v[38:39], v[94:95]
	v_lshlrev_b32_e32 v34, 16, v52
	v_and_b32_e32 v35, 0xffff0000, v52
	v_lshlrev_b32_e32 v36, 16, v56
	v_and_b32_e32 v37, 0xffff0000, v56
	v_pk_mul_f32 v[34:35], v[34:35], v[36:37]
	v_pk_fma_f32 v[96:97], v[62:63], v[34:35], v[96:97]
	v_lshlrev_b32_e32 v38, 16, v53
	v_and_b32_e32 v39, 0xffff0000, v53
	v_lshlrev_b32_e32 v40, 16, v57
	v_and_b32_e32 v41, 0xffff0000, v57
	v_pk_mul_f32 v[38:39], v[38:39], v[40:41]
	v_pk_fma_f32 v[98:99], v[64:65], v[38:39], v[98:99]
	v_lshlrev_b32_e32 v34, 16, v70
	v_and_b32_e32 v35, 0xffff0000, v70
	v_lshlrev_b32_e32 v36, 16, v66
	v_and_b32_e32 v37, 0xffff0000, v66
	v_pk_mul_f32 v[34:35], v[34:35], v[36:37]
	v_pk_fma_f32 v[92:93], v[80:81], v[34:35], v[92:93]
	v_lshlrev_b32_e32 v38, 16, v71
	v_and_b32_e32 v39, 0xffff0000, v71
	v_lshlrev_b32_e32 v40, 16, v67
	v_and_b32_e32 v41, 0xffff0000, v67
	v_pk_mul_f32 v[38:39], v[38:39], v[40:41]
	v_pk_fma_f32 v[94:95], v[82:83], v[38:39], v[94:95]
	v_lshlrev_b32_e32 v34, 16, v72
	v_and_b32_e32 v35, 0xffff0000, v72
	v_lshlrev_b32_e32 v36, 16, v68
	v_and_b32_e32 v37, 0xffff0000, v68
	v_pk_mul_f32 v[34:35], v[34:35], v[36:37]
	v_pk_fma_f32 v[96:97], v[76:77], v[34:35], v[96:97]
	v_lshlrev_b32_e32 v38, 16, v73
	v_and_b32_e32 v39, 0xffff0000, v73
	v_lshlrev_b32_e32 v40, 16, v69
	v_and_b32_e32 v41, 0xffff0000, v69
	v_pk_mul_f32 v[38:39], v[38:39], v[40:41]
	v_pk_fma_f32 v[98:99], v[78:79], v[38:39], v[98:99]
	v_lshlrev_b32_e32 v34, 16, v0
	v_and_b32_e32 v35, 0xffff0000, v0
	v_pk_mul_f32 v[100:101], v[92:93], v[34:35]
	v_lshlrev_b32_e32 v34, 16, v1
	v_and_b32_e32 v35, 0xffff0000, v1
	v_pk_mul_f32 v[102:103], v[94:95], v[34:35]
	v_lshlrev_b32_e32 v34, 16, v2
	v_and_b32_e32 v35, 0xffff0000, v2
	v_pk_mul_f32 v[104:105], v[96:97], v[34:35]
	v_lshlrev_b32_e32 v34, 16, v3
	v_and_b32_e32 v35, 0xffff0000, v3
	v_pk_mul_f32 v[106:107], v[98:99], v[34:35]
	v_pk_mul_f32 v[34:35], v[100:101], v[100:101]
	v_pk_mul_f32 v[36:37], v[102:103], v[102:103]
	v_add_f32_e32 v42, v34, v35
	v_add_f32_e32 v42, v36, v42
	v_pk_mul_f32 v[38:39], v[104:105], v[104:105]
	v_add_f32_e32 v42, v37, v42
	v_add_f32_e32 v42, v38, v42
	v_pk_mul_f32 v[40:41], v[106:107], v[106:107]
	v_add_f32_e32 v42, v39, v42
	v_add_f32_e32 v42, v40, v42
	v_add_f32_e32 v42, v41, v42
	ds_bpermute_b32 v43, v22, v42
	s_waitcnt lgkmcnt(0)
	v_add_f32_e32 v42, v42, v43
	ds_bpermute_b32 v43, v23, v42
	s_waitcnt lgkmcnt(0)
	v_add_f32_e32 v42, v42, v43
	ds_bpermute_b32 v43, v24, v42
	s_waitcnt lgkmcnt(0)
	v_add_f32_e32 v42, v42, v43
	ds_bpermute_b32 v43, v25, v42
	s_waitcnt lgkmcnt(0)
	v_add_f32_e32 v42, v42, v43
	v_fmamk_f32 v42, v42, 0x3c000000, v238
	v_cmp_gt_f32_e32 vcc, s66, v42
	v_mul_f32_e32 v43, 0x4b800000, v42
	s_nop 0
	v_cndmask_b32_e32 v42, v42, v43, vcc
	v_rsq_f32_e32 v42, v42
	s_nop 0
	v_mul_f32_e32 v43, 0x45800000, v42
	v_cndmask_b32_e32 v42, v42, v43, vcc
	v_pk_mul_f32 v[100:101], v[100:101], v[42:43] op_sel_hi:[1,0]
	v_pk_mul_f32 v[102:103], v[102:103], v[42:43] op_sel_hi:[1,0]
	v_pk_mul_f32 v[104:105], v[104:105], v[42:43] op_sel_hi:[1,0]
	v_pk_mul_f32 v[106:107], v[106:107], v[42:43] op_sel_hi:[1,0]
	v_pk_mul_f32 v[100:101], v[88:89], v[100:101]
	v_pk_mul_f32 v[102:103], v[90:91], v[102:103]
	v_pk_mul_f32 v[104:105], v[84:85], v[104:105]
	v_pk_mul_f32 v[106:107], v[86:87], v[106:107]
	v_cvt_pk_bf16_f32 v0, v100, v101
	v_cvt_pk_bf16_f32 v1, v102, v103
	v_cvt_pk_bf16_f32 v2, v104, v105
	v_cvt_pk_bf16_f32 v3, v106, v107
	global_store_dwordx4 v[44:45], v[0:3], off offset:1024
	s_mov_b32 s20, 4
	s_movk_i32 s14, 0x0
	v_or_b32_e32 v44, s20, v20
	v_or_b32_e32 v6, s14, v21
	v_mov_b64_e32 v[0:1], s[6:7]
	v_mad_i64_i32 v[0:1], s[14:15], v44, s58, v[0:1]
	v_lshlrev_b32_e32 v192, 1, v6
	v_lshlrev_b32_e32 v6, 2, v6
	v_mov_b32_e32 v7, v193
	v_lshl_add_u64 v[12:13], v[0:1], 0, v[192:193]
	v_lshl_add_u64 v[14:15], s[8:9], 0, v[6:7]
	v_bitop3_b32 v5, s20, v246, v20 bitop3:0xc8
	v_mov_b64_e32 v[50:51], 0
	v_mov_b64_e32 v[52:53], 0
	v_mov_b64_e32 v[70:71], 0
	v_mov_b64_e32 v[72:73], 0
	global_load_dwordx4 v[0:3], v[12:13], off
	global_load_dwordx4 v[16:19], v[12:13], off offset:1024
	global_load_dwordx4 v[26:29], v[12:13], off offset:2048
	v_add_co_u32_e32 v8, vcc, 0x1000, v14
	s_nop 1
	v_addc_co_u32_e32 v9, vcc, 0, v15, vcc
	global_load_dwordx4 v[30:33], v[8:9], off offset:16
	global_load_dwordx4 v[8:11], v[8:9], off
	v_cmp_ne_u32_e32 vcc, 0, v5
	s_and_saveexec_b64 s[14:15], vcc
	global_load_dwordx4 v[50:53], v[12:13], off offset:-2048
	global_load_dwordx4 v[54:57], v[12:13], off offset:-1024
	global_load_dwordx4 v[58:61], v[14:15], off offset:2048
	global_load_dwordx4 v[62:65], v[14:15], off offset:2064
	s_or_b64 exec, exec, s[14:15]
	v_cmp_lt_u32_e32 vcc, 1, v5
	s_and_saveexec_b64 s[14:15], vcc
	v_add_co_u32_e32 v74, vcc, 0xfffff000, v12
	s_nop 1
	v_addc_co_u32_e32 v75, vcc, -1, v13, vcc
	global_load_dwordx4 v[66:69], v[12:13], off offset:-4096
	global_load_dwordx4 v[70:73], v[74:75], off offset:-1024
	global_load_dwordx4 v[76:79], v[14:15], off offset:16
	global_load_dwordx4 v[80:83], v[14:15], off
	s_or_b64 exec, exec, s[14:15]
	global_load_dwordx4 v[84:87], v6, s[10:11] offset:16
	global_load_dwordx4 v[88:91], v6, s[10:11]
	v_ashrrev_i32_e32 v45, 31, v44
	v_lshlrev_b64 v[44:45], 11, v[44:45]
	v_lshl_add_u64 v[44:45], s[4:5], 0, v[44:45]
	v_lshl_add_u64 v[44:45], v[44:45], 0, v[192:193]
	v_add_co_u32_e32 v44, vcc, 0xec00000, v44
	s_nop 1
	v_addc_co_u32_e32 v45, vcc, 0, v45, vcc
	s_waitcnt vmcnt(16)
	v_lshlrev_b32_e32 v34, 16, v136
	v_and_b32_e32 v35, 0xffff0000, v136
	v_lshlrev_b32_e32 v36, 16, v140
	v_and_b32_e32 v37, 0xffff0000, v140
	v_pk_mul_f32 v[34:35], v[34:35], v[36:37]
	v_pk_fma_f32 v[92:93], v[128:129], v[34:35], 0 op_sel_hi:[1,1,0]
	v_lshlrev_b32_e32 v38, 16, v137
	v_and_b32_e32 v39, 0xffff0000, v137
	v_lshlrev_b32_e32 v40, 16, v141
	v_and_b32_e32 v41, 0xffff0000, v141
	v_pk_mul_f32 v[38:39], v[38:39], v[40:41]
	v_pk_fma_f32 v[94:95], v[130:131], v[38:39], 0 op_sel_hi:[1,1,0]
	v_lshlrev_b32_e32 v34, 16, v138
	v_and_b32_e32 v35, 0xffff0000, v138
	v_lshlrev_b32_e32 v36, 16, v142
	v_and_b32_e32 v37, 0xffff0000, v142
	v_pk_mul_f32 v[34:35], v[34:35], v[36:37]
	v_pk_fma_f32 v[96:97], v[144:145], v[34:35], 0 op_sel_hi:[1,1,0]
	v_lshlrev_b32_e32 v38, 16, v139
	v_and_b32_e32 v39, 0xffff0000, v139
	v_lshlrev_b32_e32 v40, 16, v143
	v_and_b32_e32 v41, 0xffff0000, v143
	v_pk_mul_f32 v[38:39], v[38:39], v[40:41]
	v_pk_fma_f32 v[98:99], v[146:147], v[38:39], 0 op_sel_hi:[1,1,0]
	v_lshlrev_b32_e32 v34, 16, v150
	v_and_b32_e32 v35, 0xffff0000, v150
	v_lshlrev_b32_e32 v36, 16, v154
	v_and_b32_e32 v37, 0xffff0000, v154
	v_pk_mul_f32 v[34:35], v[34:35], v[36:37]
	v_pk_fma_f32 v[92:93], v[158:159], v[34:35], v[92:93]
	v_lshlrev_b32_e32 v38, 16, v151
	v_and_b32_e32 v39, 0xffff0000, v151
	v_lshlrev_b32_e32 v40, 16, v155
	v_and_b32_e32 v41, 0xffff0000, v155
	v_pk_mul_f32 v[38:39], v[38:39], v[40:41]
	v_pk_fma_f32 v[94:95], v[160:161], v[38:39], v[94:95]
	v_lshlrev_b32_e32 v34, 16, v152
	v_and_b32_e32 v35, 0xffff0000, v152
	v_lshlrev_b32_e32 v36, 16, v156
	v_and_b32_e32 v37, 0xffff0000, v156
	v_pk_mul_f32 v[34:35], v[34:35], v[36:37]
	v_pk_fma_f32 v[96:97], v[162:163], v[34:35], v[96:97]
	v_lshlrev_b32_e32 v38, 16, v153
	v_and_b32_e32 v39, 0xffff0000, v153
	v_lshlrev_b32_e32 v40, 16, v157
	v_and_b32_e32 v41, 0xffff0000, v157
	v_pk_mul_f32 v[38:39], v[38:39], v[40:41]
	v_pk_fma_f32 v[98:99], v[164:165], v[38:39], v[98:99]
	v_lshlrev_b32_e32 v34, 16, v170
	v_and_b32_e32 v35, 0xffff0000, v170
	v_lshlrev_b32_e32 v36, 16, v166
	v_and_b32_e32 v37, 0xffff0000, v166
	v_pk_mul_f32 v[34:35], v[34:35], v[36:37]
	v_pk_fma_f32 v[92:93], v[206:207], v[34:35], v[92:93]
	v_lshlrev_b32_e32 v38, 16, v171
	v_and_b32_e32 v39, 0xffff0000, v171
	v_lshlrev_b32_e32 v40, 16, v167
	v_and_b32_e32 v41, 0xffff0000, v167
	v_pk_mul_f32 v[38:39], v[38:39], v[40:41]
	v_pk_fma_f32 v[94:95], v[208:209], v[38:39], v[94:95]
	v_lshlrev_b32_e32 v34, 16, v172
	v_and_b32_e32 v35, 0xffff0000, v172
	v_lshlrev_b32_e32 v36, 16, v168
	v_and_b32_e32 v37, 0xffff0000, v168
	v_pk_mul_f32 v[34:35], v[34:35], v[36:37]
	v_pk_fma_f32 v[96:97], v[202:203], v[34:35], v[96:97]
	v_lshlrev_b32_e32 v38, 16, v173
	v_and_b32_e32 v39, 0xffff0000, v173
	v_lshlrev_b32_e32 v40, 16, v169
	v_and_b32_e32 v41, 0xffff0000, v169
	v_pk_mul_f32 v[38:39], v[38:39], v[40:41]
	v_pk_fma_f32 v[98:99], v[204:205], v[38:39], v[98:99]
	v_lshlrev_b32_e32 v34, 16, v120
	v_and_b32_e32 v35, 0xffff0000, v120
	v_pk_mul_f32 v[100:101], v[92:93], v[34:35]
	v_lshlrev_b32_e32 v34, 16, v121
	v_and_b32_e32 v35, 0xffff0000, v121
	v_pk_mul_f32 v[102:103], v[94:95], v[34:35]
	v_lshlrev_b32_e32 v34, 16, v122
	v_and_b32_e32 v35, 0xffff0000, v122
	v_pk_mul_f32 v[104:105], v[96:97], v[34:35]
	v_lshlrev_b32_e32 v34, 16, v123
	v_and_b32_e32 v35, 0xffff0000, v123
	v_pk_mul_f32 v[106:107], v[98:99], v[34:35]
	v_pk_mul_f32 v[34:35], v[100:101], v[100:101]
	v_pk_mul_f32 v[36:37], v[102:103], v[102:103]
	v_add_f32_e32 v42, v34, v35
	v_add_f32_e32 v42, v36, v42
	v_pk_mul_f32 v[38:39], v[104:105], v[104:105]
	v_add_f32_e32 v42, v37, v42
	v_add_f32_e32 v42, v38, v42
	v_pk_mul_f32 v[40:41], v[106:107], v[106:107]
	v_add_f32_e32 v42, v39, v42
	v_add_f32_e32 v42, v40, v42
	v_add_f32_e32 v42, v41, v42
	ds_bpermute_b32 v43, v22, v42
	s_waitcnt lgkmcnt(0)
	v_add_f32_e32 v42, v42, v43
	ds_bpermute_b32 v43, v23, v42
	s_waitcnt lgkmcnt(0)
	v_add_f32_e32 v42, v42, v43
	ds_bpermute_b32 v43, v24, v42
	s_waitcnt lgkmcnt(0)
	v_add_f32_e32 v42, v42, v43
	ds_bpermute_b32 v43, v25, v42
	s_waitcnt lgkmcnt(0)
	v_add_f32_e32 v42, v42, v43
	v_fmamk_f32 v42, v42, 0x3c000000, v238
	v_cmp_gt_f32_e32 vcc, s66, v42
	v_mul_f32_e32 v43, 0x4b800000, v42
	s_nop 0
	v_cndmask_b32_e32 v42, v42, v43, vcc
	v_rsq_f32_e32 v42, v42
	s_nop 0
	v_mul_f32_e32 v43, 0x45800000, v42
	v_cndmask_b32_e32 v42, v42, v43, vcc
	v_pk_mul_f32 v[100:101], v[100:101], v[42:43] op_sel_hi:[1,0]
	v_pk_mul_f32 v[102:103], v[102:103], v[42:43] op_sel_hi:[1,0]
	v_pk_mul_f32 v[104:105], v[104:105], v[42:43] op_sel_hi:[1,0]
	v_pk_mul_f32 v[106:107], v[106:107], v[42:43] op_sel_hi:[1,0]
	v_pk_mul_f32 v[100:101], v[214:215], v[100:101]
	v_pk_mul_f32 v[102:103], v[216:217], v[102:103]
	v_pk_mul_f32 v[104:105], v[210:211], v[104:105]
	v_pk_mul_f32 v[106:107], v[212:213], v[106:107]
	v_cvt_pk_bf16_f32 v120, v100, v101
	v_cvt_pk_bf16_f32 v121, v102, v103
	v_cvt_pk_bf16_f32 v122, v104, v105
	v_cvt_pk_bf16_f32 v123, v106, v107
	global_store_dwordx4 v[148:149], v[120:123], off offset:1024
	s_mov_b32 s20, 4
	s_movk_i32 s14, 0x80
	v_or_b32_e32 v148, s20, v20
	v_or_b32_e32 v126, s14, v21
	v_mov_b64_e32 v[120:121], s[6:7]
	v_mad_i64_i32 v[120:121], s[14:15], v148, s58, v[120:121]
	v_lshlrev_b32_e32 v192, 1, v126
	v_lshlrev_b32_e32 v126, 2, v126
	v_mov_b32_e32 v127, v193
	v_lshl_add_u64 v[132:133], v[120:121], 0, v[192:193]
	v_lshl_add_u64 v[134:135], s[8:9], 0, v[126:127]
	v_bitop3_b32 v124, s20, v246, v20 bitop3:0xc8
	v_mov_b64_e32 v[150:151], 0
	v_mov_b64_e32 v[152:153], 0
	v_mov_b64_e32 v[170:171], 0
	v_mov_b64_e32 v[172:173], 0
	global_load_dwordx4 v[120:123], v[132:133], off
	global_load_dwordx4 v[136:139], v[132:133], off offset:1024
	global_load_dwordx4 v[140:143], v[132:133], off offset:2048
	v_add_co_u32_e32 v128, vcc, 0x1000, v134
	s_nop 1
	v_addc_co_u32_e32 v129, vcc, 0, v135, vcc
	global_load_dwordx4 v[144:147], v[128:129], off offset:16
	global_load_dwordx4 v[128:131], v[128:129], off
	v_cmp_ne_u32_e32 vcc, 0, v124
	s_and_saveexec_b64 s[14:15], vcc
	global_load_dwordx4 v[150:153], v[132:133], off offset:-2048
	global_load_dwordx4 v[154:157], v[132:133], off offset:-1024
	global_load_dwordx4 v[158:161], v[134:135], off offset:2048
	global_load_dwordx4 v[162:165], v[134:135], off offset:2064
	s_or_b64 exec, exec, s[14:15]
	v_cmp_lt_u32_e32 vcc, 1, v124
	s_and_saveexec_b64 s[14:15], vcc
	v_add_co_u32_e32 v174, vcc, 0xfffff000, v132
	s_nop 1
	v_addc_co_u32_e32 v175, vcc, -1, v133, vcc
	global_load_dwordx4 v[166:169], v[132:133], off offset:-4096
	global_load_dwordx4 v[170:173], v[174:175], off offset:-1024
	global_load_dwordx4 v[202:205], v[134:135], off offset:16
	global_load_dwordx4 v[206:209], v[134:135], off
	s_or_b64 exec, exec, s[14:15]
	global_load_dwordx4 v[210:213], v126, s[10:11] offset:16
	global_load_dwordx4 v[214:217], v126, s[10:11]
	v_ashrrev_i32_e32 v149, 31, v148
	v_lshlrev_b64 v[148:149], 11, v[148:149]
	v_lshl_add_u64 v[148:149], s[4:5], 0, v[148:149]
	v_lshl_add_u64 v[148:149], v[148:149], 0, v[192:193]
	v_add_co_u32_e32 v148, vcc, 0xec00000, v148
	s_nop 1
	v_addc_co_u32_e32 v149, vcc, 0, v149, vcc
	s_waitcnt vmcnt(16)
	v_lshlrev_b32_e32 v34, 16, v16
	v_and_b32_e32 v35, 0xffff0000, v16
	v_lshlrev_b32_e32 v36, 16, v26
	v_and_b32_e32 v37, 0xffff0000, v26
	v_pk_mul_f32 v[34:35], v[34:35], v[36:37]
	v_pk_fma_f32 v[92:93], v[8:9], v[34:35], 0 op_sel_hi:[1,1,0]
	v_lshlrev_b32_e32 v38, 16, v17
	v_and_b32_e32 v39, 0xffff0000, v17
	v_lshlrev_b32_e32 v40, 16, v27
	v_and_b32_e32 v41, 0xffff0000, v27
	v_pk_mul_f32 v[38:39], v[38:39], v[40:41]
	v_pk_fma_f32 v[94:95], v[10:11], v[38:39], 0 op_sel_hi:[1,1,0]
	v_lshlrev_b32_e32 v34, 16, v18
	v_and_b32_e32 v35, 0xffff0000, v18
	v_lshlrev_b32_e32 v36, 16, v28
	v_and_b32_e32 v37, 0xffff0000, v28
	v_pk_mul_f32 v[34:35], v[34:35], v[36:37]
	v_pk_fma_f32 v[96:97], v[30:31], v[34:35], 0 op_sel_hi:[1,1,0]
	v_lshlrev_b32_e32 v38, 16, v19
	v_and_b32_e32 v39, 0xffff0000, v19
	v_lshlrev_b32_e32 v40, 16, v29
	v_and_b32_e32 v41, 0xffff0000, v29
	v_pk_mul_f32 v[38:39], v[38:39], v[40:41]
	v_pk_fma_f32 v[98:99], v[32:33], v[38:39], 0 op_sel_hi:[1,1,0]
	v_lshlrev_b32_e32 v34, 16, v50
	v_and_b32_e32 v35, 0xffff0000, v50
	v_lshlrev_b32_e32 v36, 16, v54
	v_and_b32_e32 v37, 0xffff0000, v54
	v_pk_mul_f32 v[34:35], v[34:35], v[36:37]
	v_pk_fma_f32 v[92:93], v[58:59], v[34:35], v[92:93]
	v_lshlrev_b32_e32 v38, 16, v51
	v_and_b32_e32 v39, 0xffff0000, v51
	v_lshlrev_b32_e32 v40, 16, v55
	v_and_b32_e32 v41, 0xffff0000, v55
	v_pk_mul_f32 v[38:39], v[38:39], v[40:41]
	v_pk_fma_f32 v[94:95], v[60:61], v[38:39], v[94:95]
	v_lshlrev_b32_e32 v34, 16, v52
	v_and_b32_e32 v35, 0xffff0000, v52
	v_lshlrev_b32_e32 v36, 16, v56
	v_and_b32_e32 v37, 0xffff0000, v56
	v_pk_mul_f32 v[34:35], v[34:35], v[36:37]
	v_pk_fma_f32 v[96:97], v[62:63], v[34:35], v[96:97]
	v_lshlrev_b32_e32 v38, 16, v53
	v_and_b32_e32 v39, 0xffff0000, v53
	v_lshlrev_b32_e32 v40, 16, v57
	v_and_b32_e32 v41, 0xffff0000, v57
	v_pk_mul_f32 v[38:39], v[38:39], v[40:41]
	v_pk_fma_f32 v[98:99], v[64:65], v[38:39], v[98:99]
	v_lshlrev_b32_e32 v34, 16, v70
	v_and_b32_e32 v35, 0xffff0000, v70
	v_lshlrev_b32_e32 v36, 16, v66
	v_and_b32_e32 v37, 0xffff0000, v66
	v_pk_mul_f32 v[34:35], v[34:35], v[36:37]
	v_pk_fma_f32 v[92:93], v[80:81], v[34:35], v[92:93]
	v_lshlrev_b32_e32 v38, 16, v71
	v_and_b32_e32 v39, 0xffff0000, v71
	v_lshlrev_b32_e32 v40, 16, v67
	v_and_b32_e32 v41, 0xffff0000, v67
	v_pk_mul_f32 v[38:39], v[38:39], v[40:41]
	v_pk_fma_f32 v[94:95], v[82:83], v[38:39], v[94:95]
	v_lshlrev_b32_e32 v34, 16, v72
	v_and_b32_e32 v35, 0xffff0000, v72
	v_lshlrev_b32_e32 v36, 16, v68
	v_and_b32_e32 v37, 0xffff0000, v68
	v_pk_mul_f32 v[34:35], v[34:35], v[36:37]
	v_pk_fma_f32 v[96:97], v[76:77], v[34:35], v[96:97]
	v_lshlrev_b32_e32 v38, 16, v73
	v_and_b32_e32 v39, 0xffff0000, v73
	v_lshlrev_b32_e32 v40, 16, v69
	v_and_b32_e32 v41, 0xffff0000, v69
	v_pk_mul_f32 v[38:39], v[38:39], v[40:41]
	v_pk_fma_f32 v[98:99], v[78:79], v[38:39], v[98:99]
	v_lshlrev_b32_e32 v34, 16, v0
	v_and_b32_e32 v35, 0xffff0000, v0
	v_pk_mul_f32 v[100:101], v[92:93], v[34:35]
	v_lshlrev_b32_e32 v34, 16, v1
	v_and_b32_e32 v35, 0xffff0000, v1
	v_pk_mul_f32 v[102:103], v[94:95], v[34:35]
	v_lshlrev_b32_e32 v34, 16, v2
	v_and_b32_e32 v35, 0xffff0000, v2
	v_pk_mul_f32 v[104:105], v[96:97], v[34:35]
	v_lshlrev_b32_e32 v34, 16, v3
	v_and_b32_e32 v35, 0xffff0000, v3
	v_pk_mul_f32 v[106:107], v[98:99], v[34:35]
	v_pk_mul_f32 v[34:35], v[100:101], v[100:101]
	v_pk_mul_f32 v[36:37], v[102:103], v[102:103]
	v_add_f32_e32 v42, v34, v35
	v_add_f32_e32 v42, v36, v42
	v_pk_mul_f32 v[38:39], v[104:105], v[104:105]
	v_add_f32_e32 v42, v37, v42
	v_add_f32_e32 v42, v38, v42
	v_pk_mul_f32 v[40:41], v[106:107], v[106:107]
	v_add_f32_e32 v42, v39, v42
	v_add_f32_e32 v42, v40, v42
	v_add_f32_e32 v42, v41, v42
	ds_bpermute_b32 v43, v22, v42
	s_waitcnt lgkmcnt(0)
	v_add_f32_e32 v42, v42, v43
	ds_bpermute_b32 v43, v23, v42
	s_waitcnt lgkmcnt(0)
	v_add_f32_e32 v42, v42, v43
	ds_bpermute_b32 v43, v24, v42
	s_waitcnt lgkmcnt(0)
	v_add_f32_e32 v42, v42, v43
	ds_bpermute_b32 v43, v25, v42
	s_waitcnt lgkmcnt(0)
	v_add_f32_e32 v42, v42, v43
	v_fmamk_f32 v42, v42, 0x3c000000, v238
	v_cmp_gt_f32_e32 vcc, s66, v42
	v_mul_f32_e32 v43, 0x4b800000, v42
	s_nop 0
	v_cndmask_b32_e32 v42, v42, v43, vcc
	v_rsq_f32_e32 v42, v42
	s_nop 0
	v_mul_f32_e32 v43, 0x45800000, v42
	v_cndmask_b32_e32 v42, v42, v43, vcc
	v_pk_mul_f32 v[100:101], v[100:101], v[42:43] op_sel_hi:[1,0]
	v_pk_mul_f32 v[102:103], v[102:103], v[42:43] op_sel_hi:[1,0]
	v_pk_mul_f32 v[104:105], v[104:105], v[42:43] op_sel_hi:[1,0]
	v_pk_mul_f32 v[106:107], v[106:107], v[42:43] op_sel_hi:[1,0]
	v_pk_mul_f32 v[100:101], v[88:89], v[100:101]
	v_pk_mul_f32 v[102:103], v[90:91], v[102:103]
	v_pk_mul_f32 v[104:105], v[84:85], v[104:105]
	v_pk_mul_f32 v[106:107], v[86:87], v[106:107]
	v_cvt_pk_bf16_f32 v0, v100, v101
	v_cvt_pk_bf16_f32 v1, v102, v103
	v_cvt_pk_bf16_f32 v2, v104, v105
	v_cvt_pk_bf16_f32 v3, v106, v107
	global_store_dwordx4 v[44:45], v[0:3], off offset:1024
	s_mov_b32 s20, 4
	s_movk_i32 s14, 0x100
	v_or_b32_e32 v44, s20, v20
	v_or_b32_e32 v6, s14, v21
	v_mov_b64_e32 v[0:1], s[6:7]
	v_mad_i64_i32 v[0:1], s[14:15], v44, s58, v[0:1]
	v_lshlrev_b32_e32 v192, 1, v6
	v_lshlrev_b32_e32 v6, 2, v6
	v_mov_b32_e32 v7, v193
	v_lshl_add_u64 v[12:13], v[0:1], 0, v[192:193]
	v_lshl_add_u64 v[14:15], s[8:9], 0, v[6:7]
	v_bitop3_b32 v5, s20, v246, v20 bitop3:0xc8
	v_mov_b64_e32 v[50:51], 0
	v_mov_b64_e32 v[52:53], 0
	v_mov_b64_e32 v[70:71], 0
	v_mov_b64_e32 v[72:73], 0
	global_load_dwordx4 v[0:3], v[12:13], off
	global_load_dwordx4 v[16:19], v[12:13], off offset:1024
	global_load_dwordx4 v[26:29], v[12:13], off offset:2048
	v_add_co_u32_e32 v8, vcc, 0x1000, v14
	s_nop 1
	v_addc_co_u32_e32 v9, vcc, 0, v15, vcc
	global_load_dwordx4 v[30:33], v[8:9], off offset:16
	global_load_dwordx4 v[8:11], v[8:9], off
	v_cmp_ne_u32_e32 vcc, 0, v5
	s_and_saveexec_b64 s[14:15], vcc
	global_load_dwordx4 v[50:53], v[12:13], off offset:-2048
	global_load_dwordx4 v[54:57], v[12:13], off offset:-1024
	global_load_dwordx4 v[58:61], v[14:15], off offset:2048
	global_load_dwordx4 v[62:65], v[14:15], off offset:2064
	s_or_b64 exec, exec, s[14:15]
	v_cmp_lt_u32_e32 vcc, 1, v5
	s_and_saveexec_b64 s[14:15], vcc
	v_add_co_u32_e32 v74, vcc, 0xfffff000, v12
	s_nop 1
	v_addc_co_u32_e32 v75, vcc, -1, v13, vcc
	global_load_dwordx4 v[66:69], v[12:13], off offset:-4096
	global_load_dwordx4 v[70:73], v[74:75], off offset:-1024
	global_load_dwordx4 v[76:79], v[14:15], off offset:16
	global_load_dwordx4 v[80:83], v[14:15], off
	s_or_b64 exec, exec, s[14:15]
	global_load_dwordx4 v[84:87], v6, s[10:11] offset:16
	global_load_dwordx4 v[88:91], v6, s[10:11]
	v_ashrrev_i32_e32 v45, 31, v44
	v_lshlrev_b64 v[44:45], 11, v[44:45]
	v_lshl_add_u64 v[44:45], s[4:5], 0, v[44:45]
	v_lshl_add_u64 v[44:45], v[44:45], 0, v[192:193]
	v_add_co_u32_e32 v44, vcc, 0xec00000, v44
	s_nop 1
	v_addc_co_u32_e32 v45, vcc, 0, v45, vcc
	s_waitcnt vmcnt(16)
	v_lshlrev_b32_e32 v34, 16, v136
	v_and_b32_e32 v35, 0xffff0000, v136
	v_lshlrev_b32_e32 v36, 16, v140
	v_and_b32_e32 v37, 0xffff0000, v140
	v_pk_mul_f32 v[34:35], v[34:35], v[36:37]
	v_pk_fma_f32 v[92:93], v[128:129], v[34:35], 0 op_sel_hi:[1,1,0]
	v_lshlrev_b32_e32 v38, 16, v137
	v_and_b32_e32 v39, 0xffff0000, v137
	v_lshlrev_b32_e32 v40, 16, v141
	v_and_b32_e32 v41, 0xffff0000, v141
	v_pk_mul_f32 v[38:39], v[38:39], v[40:41]
	v_pk_fma_f32 v[94:95], v[130:131], v[38:39], 0 op_sel_hi:[1,1,0]
	v_lshlrev_b32_e32 v34, 16, v138
	v_and_b32_e32 v35, 0xffff0000, v138
	v_lshlrev_b32_e32 v36, 16, v142
	v_and_b32_e32 v37, 0xffff0000, v142
	v_pk_mul_f32 v[34:35], v[34:35], v[36:37]
	v_pk_fma_f32 v[96:97], v[144:145], v[34:35], 0 op_sel_hi:[1,1,0]
	v_lshlrev_b32_e32 v38, 16, v139
	v_and_b32_e32 v39, 0xffff0000, v139
	v_lshlrev_b32_e32 v40, 16, v143
	v_and_b32_e32 v41, 0xffff0000, v143
	v_pk_mul_f32 v[38:39], v[38:39], v[40:41]
	v_pk_fma_f32 v[98:99], v[146:147], v[38:39], 0 op_sel_hi:[1,1,0]
	v_lshlrev_b32_e32 v34, 16, v150
	v_and_b32_e32 v35, 0xffff0000, v150
	v_lshlrev_b32_e32 v36, 16, v154
	v_and_b32_e32 v37, 0xffff0000, v154
	v_pk_mul_f32 v[34:35], v[34:35], v[36:37]
	v_pk_fma_f32 v[92:93], v[158:159], v[34:35], v[92:93]
	v_lshlrev_b32_e32 v38, 16, v151
	v_and_b32_e32 v39, 0xffff0000, v151
	v_lshlrev_b32_e32 v40, 16, v155
	v_and_b32_e32 v41, 0xffff0000, v155
	v_pk_mul_f32 v[38:39], v[38:39], v[40:41]
	v_pk_fma_f32 v[94:95], v[160:161], v[38:39], v[94:95]
	v_lshlrev_b32_e32 v34, 16, v152
	v_and_b32_e32 v35, 0xffff0000, v152
	v_lshlrev_b32_e32 v36, 16, v156
	v_and_b32_e32 v37, 0xffff0000, v156
	v_pk_mul_f32 v[34:35], v[34:35], v[36:37]
	v_pk_fma_f32 v[96:97], v[162:163], v[34:35], v[96:97]
	v_lshlrev_b32_e32 v38, 16, v153
	v_and_b32_e32 v39, 0xffff0000, v153
	v_lshlrev_b32_e32 v40, 16, v157
	v_and_b32_e32 v41, 0xffff0000, v157
	v_pk_mul_f32 v[38:39], v[38:39], v[40:41]
	v_pk_fma_f32 v[98:99], v[164:165], v[38:39], v[98:99]
	v_lshlrev_b32_e32 v34, 16, v170
	v_and_b32_e32 v35, 0xffff0000, v170
	v_lshlrev_b32_e32 v36, 16, v166
	v_and_b32_e32 v37, 0xffff0000, v166
	v_pk_mul_f32 v[34:35], v[34:35], v[36:37]
	v_pk_fma_f32 v[92:93], v[206:207], v[34:35], v[92:93]
	v_lshlrev_b32_e32 v38, 16, v171
	v_and_b32_e32 v39, 0xffff0000, v171
	v_lshlrev_b32_e32 v40, 16, v167
	v_and_b32_e32 v41, 0xffff0000, v167
	v_pk_mul_f32 v[38:39], v[38:39], v[40:41]
	v_pk_fma_f32 v[94:95], v[208:209], v[38:39], v[94:95]
	v_lshlrev_b32_e32 v34, 16, v172
	v_and_b32_e32 v35, 0xffff0000, v172
	v_lshlrev_b32_e32 v36, 16, v168
	v_and_b32_e32 v37, 0xffff0000, v168
	v_pk_mul_f32 v[34:35], v[34:35], v[36:37]
	v_pk_fma_f32 v[96:97], v[202:203], v[34:35], v[96:97]
	v_lshlrev_b32_e32 v38, 16, v173
	v_and_b32_e32 v39, 0xffff0000, v173
	v_lshlrev_b32_e32 v40, 16, v169
	v_and_b32_e32 v41, 0xffff0000, v169
	v_pk_mul_f32 v[38:39], v[38:39], v[40:41]
	v_pk_fma_f32 v[98:99], v[204:205], v[38:39], v[98:99]
	v_lshlrev_b32_e32 v34, 16, v120
	v_and_b32_e32 v35, 0xffff0000, v120
	v_pk_mul_f32 v[100:101], v[92:93], v[34:35]
	v_lshlrev_b32_e32 v34, 16, v121
	v_and_b32_e32 v35, 0xffff0000, v121
	v_pk_mul_f32 v[102:103], v[94:95], v[34:35]
	v_lshlrev_b32_e32 v34, 16, v122
	v_and_b32_e32 v35, 0xffff0000, v122
	v_pk_mul_f32 v[104:105], v[96:97], v[34:35]
	v_lshlrev_b32_e32 v34, 16, v123
	v_and_b32_e32 v35, 0xffff0000, v123
	v_pk_mul_f32 v[106:107], v[98:99], v[34:35]
	v_pk_mul_f32 v[34:35], v[100:101], v[100:101]
	v_pk_mul_f32 v[36:37], v[102:103], v[102:103]
	v_add_f32_e32 v42, v34, v35
	v_add_f32_e32 v42, v36, v42
	v_pk_mul_f32 v[38:39], v[104:105], v[104:105]
	v_add_f32_e32 v42, v37, v42
	v_add_f32_e32 v42, v38, v42
	v_pk_mul_f32 v[40:41], v[106:107], v[106:107]
	v_add_f32_e32 v42, v39, v42
	v_add_f32_e32 v42, v40, v42
	v_add_f32_e32 v42, v41, v42
	ds_bpermute_b32 v43, v22, v42
	s_waitcnt lgkmcnt(0)
	v_add_f32_e32 v42, v42, v43
	ds_bpermute_b32 v43, v23, v42
	s_waitcnt lgkmcnt(0)
	v_add_f32_e32 v42, v42, v43
	ds_bpermute_b32 v43, v24, v42
	s_waitcnt lgkmcnt(0)
	v_add_f32_e32 v42, v42, v43
	ds_bpermute_b32 v43, v25, v42
	s_waitcnt lgkmcnt(0)
	v_add_f32_e32 v42, v42, v43
	v_fmamk_f32 v42, v42, 0x3c000000, v238
	v_cmp_gt_f32_e32 vcc, s66, v42
	v_mul_f32_e32 v43, 0x4b800000, v42
	s_nop 0
	v_cndmask_b32_e32 v42, v42, v43, vcc
	v_rsq_f32_e32 v42, v42
	s_nop 0
	v_mul_f32_e32 v43, 0x45800000, v42
	v_cndmask_b32_e32 v42, v42, v43, vcc
	v_pk_mul_f32 v[100:101], v[100:101], v[42:43] op_sel_hi:[1,0]
	v_pk_mul_f32 v[102:103], v[102:103], v[42:43] op_sel_hi:[1,0]
	v_pk_mul_f32 v[104:105], v[104:105], v[42:43] op_sel_hi:[1,0]
	v_pk_mul_f32 v[106:107], v[106:107], v[42:43] op_sel_hi:[1,0]
	v_pk_mul_f32 v[100:101], v[214:215], v[100:101]
	v_pk_mul_f32 v[102:103], v[216:217], v[102:103]
	v_pk_mul_f32 v[104:105], v[210:211], v[104:105]
	v_pk_mul_f32 v[106:107], v[212:213], v[106:107]
	v_cvt_pk_bf16_f32 v120, v100, v101
	v_cvt_pk_bf16_f32 v121, v102, v103
	v_cvt_pk_bf16_f32 v122, v104, v105
	v_cvt_pk_bf16_f32 v123, v106, v107
	global_store_dwordx4 v[148:149], v[120:123], off offset:1024
	s_mov_b32 s20, 4
	s_movk_i32 s14, 0x180
	v_or_b32_e32 v148, s20, v20
	v_or_b32_e32 v126, s14, v21
	v_mov_b64_e32 v[120:121], s[6:7]
	v_mad_i64_i32 v[120:121], s[14:15], v148, s58, v[120:121]
	v_lshlrev_b32_e32 v192, 1, v126
	v_lshlrev_b32_e32 v126, 2, v126
	v_mov_b32_e32 v127, v193
	v_lshl_add_u64 v[132:133], v[120:121], 0, v[192:193]
	v_lshl_add_u64 v[134:135], s[8:9], 0, v[126:127]
	v_bitop3_b32 v124, s20, v246, v20 bitop3:0xc8
	v_mov_b64_e32 v[150:151], 0
	v_mov_b64_e32 v[152:153], 0
	v_mov_b64_e32 v[170:171], 0
	v_mov_b64_e32 v[172:173], 0
	global_load_dwordx4 v[120:123], v[132:133], off
	global_load_dwordx4 v[136:139], v[132:133], off offset:1024
	global_load_dwordx4 v[140:143], v[132:133], off offset:2048
	v_add_co_u32_e32 v128, vcc, 0x1000, v134
	s_nop 1
	v_addc_co_u32_e32 v129, vcc, 0, v135, vcc
	global_load_dwordx4 v[144:147], v[128:129], off offset:16
	global_load_dwordx4 v[128:131], v[128:129], off
	v_cmp_ne_u32_e32 vcc, 0, v124
	s_and_saveexec_b64 s[14:15], vcc
	global_load_dwordx4 v[150:153], v[132:133], off offset:-2048
	global_load_dwordx4 v[154:157], v[132:133], off offset:-1024
	global_load_dwordx4 v[158:161], v[134:135], off offset:2048
	global_load_dwordx4 v[162:165], v[134:135], off offset:2064
	s_or_b64 exec, exec, s[14:15]
	v_cmp_lt_u32_e32 vcc, 1, v124
	s_and_saveexec_b64 s[14:15], vcc
	v_add_co_u32_e32 v174, vcc, 0xfffff000, v132
	s_nop 1
	v_addc_co_u32_e32 v175, vcc, -1, v133, vcc
	global_load_dwordx4 v[166:169], v[132:133], off offset:-4096
	global_load_dwordx4 v[170:173], v[174:175], off offset:-1024
	global_load_dwordx4 v[202:205], v[134:135], off offset:16
	global_load_dwordx4 v[206:209], v[134:135], off
	s_or_b64 exec, exec, s[14:15]
	global_load_dwordx4 v[210:213], v126, s[10:11] offset:16
	global_load_dwordx4 v[214:217], v126, s[10:11]
	v_ashrrev_i32_e32 v149, 31, v148
	v_lshlrev_b64 v[148:149], 11, v[148:149]
	v_lshl_add_u64 v[148:149], s[4:5], 0, v[148:149]
	v_lshl_add_u64 v[148:149], v[148:149], 0, v[192:193]
	v_add_co_u32_e32 v148, vcc, 0xec00000, v148
	s_nop 1
	v_addc_co_u32_e32 v149, vcc, 0, v149, vcc
	s_waitcnt vmcnt(16)
	v_lshlrev_b32_e32 v34, 16, v16
	v_and_b32_e32 v35, 0xffff0000, v16
	v_lshlrev_b32_e32 v36, 16, v26
	v_and_b32_e32 v37, 0xffff0000, v26
	v_pk_mul_f32 v[34:35], v[34:35], v[36:37]
	v_pk_fma_f32 v[92:93], v[8:9], v[34:35], 0 op_sel_hi:[1,1,0]
	v_lshlrev_b32_e32 v38, 16, v17
	v_and_b32_e32 v39, 0xffff0000, v17
	v_lshlrev_b32_e32 v40, 16, v27
	v_and_b32_e32 v41, 0xffff0000, v27
	v_pk_mul_f32 v[38:39], v[38:39], v[40:41]
	v_pk_fma_f32 v[94:95], v[10:11], v[38:39], 0 op_sel_hi:[1,1,0]
	v_lshlrev_b32_e32 v34, 16, v18
	v_and_b32_e32 v35, 0xffff0000, v18
	v_lshlrev_b32_e32 v36, 16, v28
	v_and_b32_e32 v37, 0xffff0000, v28
	v_pk_mul_f32 v[34:35], v[34:35], v[36:37]
	v_pk_fma_f32 v[96:97], v[30:31], v[34:35], 0 op_sel_hi:[1,1,0]
	v_lshlrev_b32_e32 v38, 16, v19
	v_and_b32_e32 v39, 0xffff0000, v19
	v_lshlrev_b32_e32 v40, 16, v29
	v_and_b32_e32 v41, 0xffff0000, v29
	v_pk_mul_f32 v[38:39], v[38:39], v[40:41]
	v_pk_fma_f32 v[98:99], v[32:33], v[38:39], 0 op_sel_hi:[1,1,0]
	v_lshlrev_b32_e32 v34, 16, v50
	v_and_b32_e32 v35, 0xffff0000, v50
	v_lshlrev_b32_e32 v36, 16, v54
	v_and_b32_e32 v37, 0xffff0000, v54
	v_pk_mul_f32 v[34:35], v[34:35], v[36:37]
	v_pk_fma_f32 v[92:93], v[58:59], v[34:35], v[92:93]
	v_lshlrev_b32_e32 v38, 16, v51
	v_and_b32_e32 v39, 0xffff0000, v51
	v_lshlrev_b32_e32 v40, 16, v55
	v_and_b32_e32 v41, 0xffff0000, v55
	v_pk_mul_f32 v[38:39], v[38:39], v[40:41]
	v_pk_fma_f32 v[94:95], v[60:61], v[38:39], v[94:95]
	v_lshlrev_b32_e32 v34, 16, v52
	v_and_b32_e32 v35, 0xffff0000, v52
	v_lshlrev_b32_e32 v36, 16, v56
	v_and_b32_e32 v37, 0xffff0000, v56
	v_pk_mul_f32 v[34:35], v[34:35], v[36:37]
	v_pk_fma_f32 v[96:97], v[62:63], v[34:35], v[96:97]
	v_lshlrev_b32_e32 v38, 16, v53
	v_and_b32_e32 v39, 0xffff0000, v53
	v_lshlrev_b32_e32 v40, 16, v57
	v_and_b32_e32 v41, 0xffff0000, v57
	v_pk_mul_f32 v[38:39], v[38:39], v[40:41]
	v_pk_fma_f32 v[98:99], v[64:65], v[38:39], v[98:99]
	v_lshlrev_b32_e32 v34, 16, v70
	v_and_b32_e32 v35, 0xffff0000, v70
	v_lshlrev_b32_e32 v36, 16, v66
	v_and_b32_e32 v37, 0xffff0000, v66
	v_pk_mul_f32 v[34:35], v[34:35], v[36:37]
	v_pk_fma_f32 v[92:93], v[80:81], v[34:35], v[92:93]
	v_lshlrev_b32_e32 v38, 16, v71
	v_and_b32_e32 v39, 0xffff0000, v71
	v_lshlrev_b32_e32 v40, 16, v67
	v_and_b32_e32 v41, 0xffff0000, v67
	v_pk_mul_f32 v[38:39], v[38:39], v[40:41]
	v_pk_fma_f32 v[94:95], v[82:83], v[38:39], v[94:95]
	v_lshlrev_b32_e32 v34, 16, v72
	v_and_b32_e32 v35, 0xffff0000, v72
	v_lshlrev_b32_e32 v36, 16, v68
	v_and_b32_e32 v37, 0xffff0000, v68
	v_pk_mul_f32 v[34:35], v[34:35], v[36:37]
	v_pk_fma_f32 v[96:97], v[76:77], v[34:35], v[96:97]
	v_lshlrev_b32_e32 v38, 16, v73
	v_and_b32_e32 v39, 0xffff0000, v73
	v_lshlrev_b32_e32 v40, 16, v69
	v_and_b32_e32 v41, 0xffff0000, v69
	v_pk_mul_f32 v[38:39], v[38:39], v[40:41]
	v_pk_fma_f32 v[98:99], v[78:79], v[38:39], v[98:99]
	v_lshlrev_b32_e32 v34, 16, v0
	v_and_b32_e32 v35, 0xffff0000, v0
	v_pk_mul_f32 v[100:101], v[92:93], v[34:35]
	v_lshlrev_b32_e32 v34, 16, v1
	v_and_b32_e32 v35, 0xffff0000, v1
	v_pk_mul_f32 v[102:103], v[94:95], v[34:35]
	v_lshlrev_b32_e32 v34, 16, v2
	v_and_b32_e32 v35, 0xffff0000, v2
	v_pk_mul_f32 v[104:105], v[96:97], v[34:35]
	v_lshlrev_b32_e32 v34, 16, v3
	v_and_b32_e32 v35, 0xffff0000, v3
	v_pk_mul_f32 v[106:107], v[98:99], v[34:35]
	v_pk_mul_f32 v[34:35], v[100:101], v[100:101]
	v_pk_mul_f32 v[36:37], v[102:103], v[102:103]
	v_add_f32_e32 v42, v34, v35
	v_add_f32_e32 v42, v36, v42
	v_pk_mul_f32 v[38:39], v[104:105], v[104:105]
	v_add_f32_e32 v42, v37, v42
	v_add_f32_e32 v42, v38, v42
	v_pk_mul_f32 v[40:41], v[106:107], v[106:107]
	v_add_f32_e32 v42, v39, v42
	v_add_f32_e32 v42, v40, v42
	v_add_f32_e32 v42, v41, v42
	ds_bpermute_b32 v43, v22, v42
	s_waitcnt lgkmcnt(0)
	v_add_f32_e32 v42, v42, v43
	ds_bpermute_b32 v43, v23, v42
	s_waitcnt lgkmcnt(0)
	v_add_f32_e32 v42, v42, v43
	ds_bpermute_b32 v43, v24, v42
	s_waitcnt lgkmcnt(0)
	v_add_f32_e32 v42, v42, v43
	ds_bpermute_b32 v43, v25, v42
	s_waitcnt lgkmcnt(0)
	v_add_f32_e32 v42, v42, v43
	v_fmamk_f32 v42, v42, 0x3c000000, v238
	v_cmp_gt_f32_e32 vcc, s66, v42
	v_mul_f32_e32 v43, 0x4b800000, v42
	s_nop 0
	v_cndmask_b32_e32 v42, v42, v43, vcc
	v_rsq_f32_e32 v42, v42
	s_nop 0
	v_mul_f32_e32 v43, 0x45800000, v42
	v_cndmask_b32_e32 v42, v42, v43, vcc
	v_pk_mul_f32 v[100:101], v[100:101], v[42:43] op_sel_hi:[1,0]
	v_pk_mul_f32 v[102:103], v[102:103], v[42:43] op_sel_hi:[1,0]
	v_pk_mul_f32 v[104:105], v[104:105], v[42:43] op_sel_hi:[1,0]
	v_pk_mul_f32 v[106:107], v[106:107], v[42:43] op_sel_hi:[1,0]
	v_pk_mul_f32 v[100:101], v[88:89], v[100:101]
	v_pk_mul_f32 v[102:103], v[90:91], v[102:103]
	v_pk_mul_f32 v[104:105], v[84:85], v[104:105]
	v_pk_mul_f32 v[106:107], v[86:87], v[106:107]
	v_cvt_pk_bf16_f32 v0, v100, v101
	v_cvt_pk_bf16_f32 v1, v102, v103
	v_cvt_pk_bf16_f32 v2, v104, v105
	v_cvt_pk_bf16_f32 v3, v106, v107
	global_store_dwordx4 v[44:45], v[0:3], off offset:1024
	s_waitcnt vmcnt(1)
	v_lshlrev_b32_e32 v34, 16, v136
	v_and_b32_e32 v35, 0xffff0000, v136
	v_lshlrev_b32_e32 v36, 16, v140
	v_and_b32_e32 v37, 0xffff0000, v140
	v_pk_mul_f32 v[34:35], v[34:35], v[36:37]
	v_pk_fma_f32 v[92:93], v[128:129], v[34:35], 0 op_sel_hi:[1,1,0]
	v_lshlrev_b32_e32 v38, 16, v137
	v_and_b32_e32 v39, 0xffff0000, v137
	v_lshlrev_b32_e32 v40, 16, v141
	v_and_b32_e32 v41, 0xffff0000, v141
	v_pk_mul_f32 v[38:39], v[38:39], v[40:41]
	v_pk_fma_f32 v[94:95], v[130:131], v[38:39], 0 op_sel_hi:[1,1,0]
	v_lshlrev_b32_e32 v34, 16, v138
	v_and_b32_e32 v35, 0xffff0000, v138
	v_lshlrev_b32_e32 v36, 16, v142
	v_and_b32_e32 v37, 0xffff0000, v142
	v_pk_mul_f32 v[34:35], v[34:35], v[36:37]
	v_pk_fma_f32 v[96:97], v[144:145], v[34:35], 0 op_sel_hi:[1,1,0]
	v_lshlrev_b32_e32 v38, 16, v139
	v_and_b32_e32 v39, 0xffff0000, v139
	v_lshlrev_b32_e32 v40, 16, v143
	v_and_b32_e32 v41, 0xffff0000, v143
	v_pk_mul_f32 v[38:39], v[38:39], v[40:41]
	v_pk_fma_f32 v[98:99], v[146:147], v[38:39], 0 op_sel_hi:[1,1,0]
	v_lshlrev_b32_e32 v34, 16, v150
	v_and_b32_e32 v35, 0xffff0000, v150
	v_lshlrev_b32_e32 v36, 16, v154
	v_and_b32_e32 v37, 0xffff0000, v154
	v_pk_mul_f32 v[34:35], v[34:35], v[36:37]
	v_pk_fma_f32 v[92:93], v[158:159], v[34:35], v[92:93]
	v_lshlrev_b32_e32 v38, 16, v151
	v_and_b32_e32 v39, 0xffff0000, v151
	v_lshlrev_b32_e32 v40, 16, v155
	v_and_b32_e32 v41, 0xffff0000, v155
	v_pk_mul_f32 v[38:39], v[38:39], v[40:41]
	v_pk_fma_f32 v[94:95], v[160:161], v[38:39], v[94:95]
	v_lshlrev_b32_e32 v34, 16, v152
	v_and_b32_e32 v35, 0xffff0000, v152
	v_lshlrev_b32_e32 v36, 16, v156
	v_and_b32_e32 v37, 0xffff0000, v156
	v_pk_mul_f32 v[34:35], v[34:35], v[36:37]
	v_pk_fma_f32 v[96:97], v[162:163], v[34:35], v[96:97]
	v_lshlrev_b32_e32 v38, 16, v153
	v_and_b32_e32 v39, 0xffff0000, v153
	v_lshlrev_b32_e32 v40, 16, v157
	v_and_b32_e32 v41, 0xffff0000, v157
	v_pk_mul_f32 v[38:39], v[38:39], v[40:41]
	v_pk_fma_f32 v[98:99], v[164:165], v[38:39], v[98:99]
	v_lshlrev_b32_e32 v34, 16, v170
	v_and_b32_e32 v35, 0xffff0000, v170
	v_lshlrev_b32_e32 v36, 16, v166
	v_and_b32_e32 v37, 0xffff0000, v166
	v_pk_mul_f32 v[34:35], v[34:35], v[36:37]
	v_pk_fma_f32 v[92:93], v[206:207], v[34:35], v[92:93]
	v_lshlrev_b32_e32 v38, 16, v171
	v_and_b32_e32 v39, 0xffff0000, v171
	v_lshlrev_b32_e32 v40, 16, v167
	v_and_b32_e32 v41, 0xffff0000, v167
	v_pk_mul_f32 v[38:39], v[38:39], v[40:41]
	v_pk_fma_f32 v[94:95], v[208:209], v[38:39], v[94:95]
	v_lshlrev_b32_e32 v34, 16, v172
	v_and_b32_e32 v35, 0xffff0000, v172
	v_lshlrev_b32_e32 v36, 16, v168
	v_and_b32_e32 v37, 0xffff0000, v168
	v_pk_mul_f32 v[34:35], v[34:35], v[36:37]
	v_pk_fma_f32 v[96:97], v[202:203], v[34:35], v[96:97]
	v_lshlrev_b32_e32 v38, 16, v173
	v_and_b32_e32 v39, 0xffff0000, v173
	v_lshlrev_b32_e32 v40, 16, v169
	v_and_b32_e32 v41, 0xffff0000, v169
	v_pk_mul_f32 v[38:39], v[38:39], v[40:41]
	v_pk_fma_f32 v[98:99], v[204:205], v[38:39], v[98:99]
	v_lshlrev_b32_e32 v34, 16, v120
	v_and_b32_e32 v35, 0xffff0000, v120
	v_pk_mul_f32 v[100:101], v[92:93], v[34:35]
	v_lshlrev_b32_e32 v34, 16, v121
	v_and_b32_e32 v35, 0xffff0000, v121
	v_pk_mul_f32 v[102:103], v[94:95], v[34:35]
	v_lshlrev_b32_e32 v34, 16, v122
	v_and_b32_e32 v35, 0xffff0000, v122
	v_pk_mul_f32 v[104:105], v[96:97], v[34:35]
	v_lshlrev_b32_e32 v34, 16, v123
	v_and_b32_e32 v35, 0xffff0000, v123
	v_pk_mul_f32 v[106:107], v[98:99], v[34:35]
	v_pk_mul_f32 v[34:35], v[100:101], v[100:101]
	v_pk_mul_f32 v[36:37], v[102:103], v[102:103]
	v_add_f32_e32 v42, v34, v35
	v_add_f32_e32 v42, v36, v42
	v_pk_mul_f32 v[38:39], v[104:105], v[104:105]
	v_add_f32_e32 v42, v37, v42
	v_add_f32_e32 v42, v38, v42
	v_pk_mul_f32 v[40:41], v[106:107], v[106:107]
	v_add_f32_e32 v42, v39, v42
	v_add_f32_e32 v42, v40, v42
	v_add_f32_e32 v42, v41, v42
	ds_bpermute_b32 v43, v22, v42
	s_waitcnt lgkmcnt(0)
	v_add_f32_e32 v42, v42, v43
	ds_bpermute_b32 v43, v23, v42
	s_waitcnt lgkmcnt(0)
	v_add_f32_e32 v42, v42, v43
	ds_bpermute_b32 v43, v24, v42
	s_waitcnt lgkmcnt(0)
	v_add_f32_e32 v42, v42, v43
	ds_bpermute_b32 v43, v25, v42
	s_waitcnt lgkmcnt(0)
	v_add_f32_e32 v42, v42, v43
	v_fmamk_f32 v42, v42, 0x3c000000, v238
	v_cmp_gt_f32_e32 vcc, s66, v42
	v_mul_f32_e32 v43, 0x4b800000, v42
	s_nop 0
	v_cndmask_b32_e32 v42, v42, v43, vcc
	v_rsq_f32_e32 v42, v42
	s_nop 0
	v_mul_f32_e32 v43, 0x45800000, v42
	v_cndmask_b32_e32 v42, v42, v43, vcc
	v_pk_mul_f32 v[100:101], v[100:101], v[42:43] op_sel_hi:[1,0]
	v_pk_mul_f32 v[102:103], v[102:103], v[42:43] op_sel_hi:[1,0]
	v_pk_mul_f32 v[104:105], v[104:105], v[42:43] op_sel_hi:[1,0]
	v_pk_mul_f32 v[106:107], v[106:107], v[42:43] op_sel_hi:[1,0]
	v_pk_mul_f32 v[100:101], v[214:215], v[100:101]
	v_pk_mul_f32 v[102:103], v[216:217], v[102:103]
	v_pk_mul_f32 v[104:105], v[210:211], v[104:105]
	v_pk_mul_f32 v[106:107], v[212:213], v[106:107]
	v_cvt_pk_bf16_f32 v120, v100, v101
	v_cvt_pk_bf16_f32 v121, v102, v103
	v_cvt_pk_bf16_f32 v122, v104, v105
	v_cvt_pk_bf16_f32 v123, v106, v107
	global_store_dwordx4 v[148:149], v[120:123], off offset:1024
	s_branch .LBB0_738
